# mixer phases 1-3: static s_setprio 1 for waves 0-3 instead of waves 4-7 (other half of the per-half A/B)
# baseline (speedup 1.0000x reference)
; #define RUN(kind, ...) do { _Pragma("nounroll") for (int rep_ = 0; rep_ < ((REP_KIND == (kind)) ? 2 : 1); ++rep_) { __VA_ARGS__; } } while (0)
; #define SEAM(k) do { if (IN((k) + 1)) { if (use_bar) { xcd_barrier(bar); if (REP_KIND == 9) xcd_barrier(bar); } else if (F.tid == 0) __hip_atomic_store(F.ctl + CW_TMO, 0xBADBA0u, RLX_AGENT); } } while (0)
; __global__ void __launch_bounds__(NWAVES * 64, 2) fwd_kernel(Args args) {
;     ...
;         if (IN(pb + 1)) { RUN(2, mixer_phase1(F, l)); SEAM(pb + 1); }
;         if (IN(pb + 2)) { mixer_phase2(F, l, 0); if (REP_KIND == 3) mixer_phase2(F, l, 1); SEAM(pb + 2); }
;         if (IN(pb + 3)) { RUN(4, mixer_phase3(F, l)); SEAM(pb + 3); }
.LBB0_404:
	s_andn2_b64 vcc, exec, s[0:1]
	s_cbranch_vccnz .LBB0_902
	v_readlane_b32 s100, v251, 40
	s_nop 0
	s_bitcmp1_b32 s100, 10
	s_cbranch_scc1 .Lprio_m1_skip
	s_setprio 1
